# static s_setprio 1 for workgroups >= 256 (second workgroup per CU)
# baseline (speedup 1.0000x reference)
; __global__ void __launch_bounds__(256, 2) mega_kernel(Params p) {
;   extern __shared__ __attribute__((aligned(16))) char smem[];
;   cg::grid_group grid = cg::this_grid();
;   const int G = gridDim.x;
;   unsigned bk = 0;
;   if (blockIdx.x == 0 && threadIdx.x < 17) __hip_atomic_store(p.bar + 64 * threadIdx.x, 0u, __ATOMIC_RELAXED, __HIP_MEMORY_SCOPE_AGENT);
_Z11mega_kernel6Params:
	s_mov_b64 s[80:81], s[0:1]
	s_mov_b32 s86, s2
	s_cmpk_ge_u32 s2, 0x100
	s_cbranch_scc0 .Lprio_skip
	s_setprio 1
.Lprio_skip:
	s_add_u32 s2, s80, 0x9e0
	s_load_dword s82, s[0:1], 0x9e0
	s_addc_u32 s3, s81, 0
	s_cmp_eq_u32 s86, 0
	v_and_b32_e32 v167, 0x3ff, v0
	s_cselect_b64 s[0:1], -1, 0
	v_cmp_gt_u32_e32 vcc, 17, v167
	s_and_b64 s[0:1], s[0:1], vcc
	s_and_saveexec_b64 s[4:5], s[0:1]
	s_cbranch_execz .LBB0_2
	s_load_dwordx2 s[0:1], s[80:81], 0xe0
	v_lshlrev_b32_e32 v1, 8, v167
	v_mov_b32_e32 v2, 0
	s_waitcnt lgkmcnt(0)
	global_store_dword v1, v2, s[0:1] sc1
